# merged->w_out barrier also a group barrier; cross-group overwrite hazard kept by a split-phase grid barrier (signal after merged GEMM, check before up GEMM)
# speedup vs baseline: 1.0233x; 1.0074x over previous
; #define LAS __attribute__((address_space(3)))
; __device__ __forceinline__ unsigned xb_add(unsigned* p, unsigned v) { return __hip_atomic_fetch_add(p, v, __ATOMIC_RELAXED, __HIP_MEMORY_SCOPE_AGENT); }
; __device__ __forceinline__ unsigned xb_xcc_id() { return (unsigned)__builtin_amdgcn_s_getreg((3 << 11) | 20) & 0xFu; }
; __device__ __forceinline__ XcdBarrier xcd_barrier_post(unsigned* bar, volatile LAS unsigned* st) {
;     XcdBarrier b; b.bar = bar; b.x = xb_xcc_id(); b.st = st;
;     if (threadIdx.x == 0) (void)xb_add(&bar[XB_XCNT(b.x)], 1u);
;     return b;
; }
; __device__ __forceinline__ void xcd_barrier(const XcdBarrier& b) {
;     asm volatile("s_waitcnt vmcnt(0)" ::: "memory");
;     __syncthreads();
;     if (threadIdx.x == 0) {
;         unsigned* bar = b.bar;
;         __builtin_amdgcn_s_waitcnt(0);
;         unsigned nloc = b.st[0], nx = b.st[1];
;         if (nloc == 0u) { xcd_barrier_complete(bar, b.x, nloc, nx); b.st[0] = nloc; b.st[1] = nx; }
;         const unsigned old = xb_add(&bar[XB_XSUB(b.x)], 1u);
.LBB0_507:
	v_readlane_b32 s18, v247, 47
	v_readlane_b32 s19, v247, 48
	s_cmp_gt_i32 s19, 4
	s_cbranch_scc0 .LBB0_561
	s_waitcnt vmcnt(0)
	s_waitcnt vmcnt(0) lgkmcnt(0)
	s_barrier
	s_mov_b64 s[0:1], exec
	v_readlane_b32 s2, v247, 37
	v_readlane_b32 s3, v247, 38
	s_and_b64 s[2:3], s[0:1], s[2:3]
	s_mov_b64 exec, s[2:3]
	s_cbranch_execz .LBB0_560
	v_readlane_b32 s2, v247, 36
	s_nop 0
	s_and_b32 s2, s2, 7
	s_lshl_b32 s2, s2, 2
	s_lshl_b32 s3, 1, s2
	v_mov_b32_e32 v2, s3
	s_and_b32 s2, s90, 31
	s_lshl_b32 s2, s2, 6
	s_add_u32 s2, s62, s2
	s_addc_u32 s3, s63, 0
	s_add_u32 s2, s2, 0xa000
	s_addc_u32 s3, s3, 0
	v_mov_b32_e32 v1, 0
	global_atomic_add v1, v2, s[2:3]
	s_add_i32 s2, 0, 0x24160
	v_mov_b32_e32 v1, s2
	s_waitcnt vmcnt(0) expcnt(0) lgkmcnt(0)
	ds_read_b32 v3, v1
	s_add_i32 s2, 0, 0x24164
	v_mov_b32_e32 v1, s2
	ds_read_b32 v1, v1
	s_waitcnt lgkmcnt(1)
	v_cmp_ne_u32_e32 vcc, 0, v3
	s_cbranch_vccnz .LBB0_524
	v_readlane_b32 s2, v247, 0
	v_readlane_b32 s3, v247, 1
	s_load_dwordx2 s[6:7], s[2:3], 0x4
	s_add_u32 s2, s62, 0x4200
	s_addc_u32 s3, s63, 0
	s_add_u32 s4, s62, 0x4400
	s_addc_u32 s5, s63, 0
	s_waitcnt lgkmcnt(0)
	s_mul_i32 s33, s6, s80
	s_add_u32 s6, s62, 0x4500
	s_mul_i32 s33, s33, s7
	s_addc_u32 s7, s63, 0
	s_add_u32 s8, s62, 0x4600
	s_addc_u32 s9, s63, 0
	s_add_u32 s10, s62, 0x4700
	s_addc_u32 s11, s63, 0
	s_add_u32 s12, s62, 0x4800
	s_addc_u32 s13, s63, 0
	s_add_u32 s14, s62, 0x4900
	s_addc_u32 s15, s63, 0
	s_add_u32 s16, s62, 0x4a00
	s_addc_u32 s17, s63, 0
	s_add_u32 s18, s62, 0x4b00
	s_addc_u32 s19, s63, 0
	s_add_u32 s20, s62, 0x4c00
	s_addc_u32 s21, s63, 0
	s_add_u32 s22, s62, 0x4d00
	s_addc_u32 s23, s63, 0
	s_add_u32 s24, s62, 0x4e00
	s_addc_u32 s25, s63, 0
	s_add_u32 s26, s62, 0x4f00
	s_addc_u32 s27, s63, 0
	s_add_u32 s28, s62, 0x5000
	s_addc_u32 s29, s63, 0
	s_add_u32 s30, s62, 0x5100
	s_addc_u32 s31, s63, 0
	s_add_u32 s34, s62, 0x5200
	s_addc_u32 s35, s63, 0
	s_add_u32 s36, s62, 0x5300
	s_addc_u32 s37, s63, 0
	s_mov_b32 s44, 1
	v_mov_b32_e32 v17, 0
	s_branch .LBB0_512

; __device__ __forceinline__ unsigned xb_ld(unsigned* p)              { return __hip_atomic_load(p, __ATOMIC_RELAXED, __HIP_MEMORY_SCOPE_AGENT); }
; __device__ __forceinline__ unsigned xb_add(unsigned* p, unsigned v) { return __hip_atomic_fetch_add(p, v, __ATOMIC_RELAXED, __HIP_MEMORY_SCOPE_AGENT); }
; #define XB_SPIN(cond, bar) do { unsigned _sp = 0; while (cond) { __builtin_amdgcn_s_sleep(1); \
;     if ((++_sp & 255u) == 0u) { if (xb_ld(&(bar)[XB_TMO])) break; if (_sp > XB_SPIN_CAP) { atomicAdd(&(bar)[XB_TMO], 1u); break; } } } } while (0)
; __device__ __forceinline__ void xcd_barrier(const XcdBarrier& b) {
;     asm volatile("s_waitcnt vmcnt(0)" ::: "memory");
;     __syncthreads();
;     if (threadIdx.x == 0) {
;         unsigned* bar = b.bar;
;         __builtin_amdgcn_s_waitcnt(0);
;         unsigned nloc = b.st[0], nx = b.st[1];
;         if (nloc == 0u) { xcd_barrier_complete(bar, b.x, nloc, nx); b.st[0] = nloc; b.st[1] = nx; }
;         const unsigned old = xb_add(&bar[XB_XSUB(b.x)], 1u);
;         const unsigned gen = old / nloc;
;         if (old + 1u == (gen + 1u) * nloc) {
;             __builtin_amdgcn_fence(__ATOMIC_RELEASE, "agent");
;             asm volatile("s_waitcnt vmcnt(0)" ::: "memory");
;             const unsigned og = xb_add(&bar[XB_TOP], 1u);
;             const unsigned tg = og / nx;
;             if (og + 1u == (tg + 1u) * nx) xb_add(&bar[XB_TOPGEN], 1u);
;             else XB_SPIN(xb_ld(&bar[XB_TOPGEN]) == tg, bar);
;             __builtin_amdgcn_fence(__ATOMIC_ACQUIRE, "agent");
;             xb_add(&bar[XB_XGEN(b.x)], 1u);
;             asm volatile("s_waitcnt vmcnt(0)" ::: "memory");
;         } else {
;             XB_SPIN(xb_ld(&bar[XB_XGEN(b.x)]) == gen, bar);
;             __builtin_amdgcn_fence(__ATOMIC_ACQUIRE, "agent");
;             asm volatile("s_waitcnt vmcnt(0)" ::: "memory");
;         }
;     }
;     __syncthreads();
; }
.LBB0_729:
	s_waitcnt vmcnt(0)
	s_waitcnt vmcnt(0) lgkmcnt(0)
	s_barrier
	s_mov_b64 s[0:1], exec
	v_readlane_b32 s2, v247, 37
	v_readlane_b32 s3, v247, 38
	s_and_b64 s[2:3], s[0:1], s[2:3]
	s_mov_b64 exec, s[2:3]
	s_cbranch_execz .LBB0_781
	v_readlane_b32 s5, v247, 36
	s_and_b32 s2, s90, 31
	s_lshl_b32 s2, s2, 6
	s_add_u32 s2, s62, s2
	s_addc_u32 s3, s63, 0
	s_add_u32 s6, s2, 0xa000
	s_addc_u32 s7, s3, 0
	s_add_u32 s2, s2, 0xb000
	s_addc_u32 s3, s3, 0
	s_and_b32 s5, s5, 7
	s_lshl_b32 s5, s5, 2
	s_lshl_b32 s5, 8, s5
	v_mov_b32_e32 v1, 0
	global_load_dword v3, v1, s[6:7] sc1
	v_mov_b32_e32 v2, 1
	s_mov_b32 s4, 0
	s_add_u32 s6, s62, 0xc000
	s_addc_u32 s7, s63, 0
	s_waitcnt vmcnt(0) lgkmcnt(0)
	v_cmp_eq_u32_e32 vcc, s5, v3
	s_cbranch_vccnz .Lgrpbar2_same
	buffer_wbl2 sc1
	s_waitcnt vmcnt(0)
.Lgrpbar2_same:
	global_atomic_add v1, v2, s[2:3]
	global_atomic_add v1, v2, s[6:7]

; __device__ __forceinline__ unsigned xb_ld(unsigned* p)              { return __hip_atomic_load(p, __ATOMIC_RELAXED, __HIP_MEMORY_SCOPE_AGENT); }
; __device__ __forceinline__ unsigned xb_add(unsigned* p, unsigned v) { return __hip_atomic_fetch_add(p, v, __ATOMIC_RELAXED, __HIP_MEMORY_SCOPE_AGENT); }
; #define XB_SPIN(cond, bar) do { unsigned _sp = 0; while (cond) { __builtin_amdgcn_s_sleep(1); \
;     if ((++_sp & 255u) == 0u) { if (xb_ld(&(bar)[XB_TMO])) break; if (_sp > XB_SPIN_CAP) { atomicAdd(&(bar)[XB_TMO], 1u); break; } } } } while (0)
; __device__ __forceinline__ void xcd_barrier(const XcdBarrier& b) {
;     asm volatile("s_waitcnt vmcnt(0)" ::: "memory");
;     __syncthreads();
;     if (threadIdx.x == 0) {
;         unsigned* bar = b.bar;
;         __builtin_amdgcn_s_waitcnt(0);
;         unsigned nloc = b.st[0], nx = b.st[1];
;         if (nloc == 0u) { xcd_barrier_complete(bar, b.x, nloc, nx); b.st[0] = nloc; b.st[1] = nx; }
;         const unsigned old = xb_add(&bar[XB_XSUB(b.x)], 1u);
;         const unsigned gen = old / nloc;
;         if (old + 1u == (gen + 1u) * nloc) {
;             __builtin_amdgcn_fence(__ATOMIC_RELEASE, "agent");
;             asm volatile("s_waitcnt vmcnt(0)" ::: "memory");
;             const unsigned og = xb_add(&bar[XB_TOP], 1u);
;             const unsigned tg = og / nx;
;             if (og + 1u == (tg + 1u) * nx) xb_add(&bar[XB_TOPGEN], 1u);
;             else XB_SPIN(xb_ld(&bar[XB_TOPGEN]) == tg, bar);
;             __builtin_amdgcn_fence(__ATOMIC_ACQUIRE, "agent");
;             xb_add(&bar[XB_XGEN(b.x)], 1u);
;             asm volatile("s_waitcnt vmcnt(0)" ::: "memory");
;         } else {
;             XB_SPIN(xb_ld(&bar[XB_XGEN(b.x)]) == gen, bar);
;             __builtin_amdgcn_fence(__ATOMIC_ACQUIRE, "agent");
;             asm volatile("s_waitcnt vmcnt(0)" ::: "memory");
;         }
;     }
;     __syncthreads();
; }
.LBB0_823:
	s_cmp_lt_i32 s19, 7
	s_cbranch_scc1 .LBB0_877
	s_waitcnt vmcnt(0)
	s_waitcnt vmcnt(0) lgkmcnt(0)
	s_barrier
	s_mov_b64 s[0:1], exec
	v_readlane_b32 s2, v247, 37
	v_readlane_b32 s3, v247, 38
	s_and_b64 s[2:3], s[0:1], s[2:3]
	s_mov_b64 exec, s[2:3]
	s_cbranch_execz .LBB0_876
	v_readlane_b32 s5, v247, 36
	s_and_b32 s2, s90, 31
	s_lshl_b32 s2, s2, 6
	s_add_u32 s2, s62, s2
	s_addc_u32 s3, s63, 0
	s_add_u32 s6, s2, 0xa000
	s_addc_u32 s7, s3, 0
	s_add_u32 s2, s2, 0x8000
	s_addc_u32 s3, s3, 0
	s_and_b32 s5, s5, 7
	s_lshl_b32 s5, s5, 2
	s_lshl_b32 s5, 8, s5
	v_mov_b32_e32 v1, 0
	global_load_dword v3, v1, s[6:7] sc1
	v_mov_b32_e32 v2, 1
	s_mov_b32 s4, 0
	s_add_u32 s6, s62, 0xc000
	s_addc_u32 s7, s63, 0
	s_waitcnt vmcnt(0) lgkmcnt(0)
	v_cmp_eq_u32_e32 vcc, s5, v3
	s_cbranch_vccnz .Lgrpbar1_same
	buffer_wbl2 sc1
	s_waitcnt vmcnt(0)

.Lgrpbar1_done:
.Lgrpbar1_gspin:
	global_load_dword v3, v1, s[6:7] sc1
	s_waitcnt vmcnt(0)
	v_cmp_lt_u32_e32 vcc, 0xff, v3
	s_cbranch_vccnz .Lgrpbar1_gdone
	s_sleep 1
	s_add_i32 s4, s4, 1
	s_cmp_lt_u32 s4, 0x200000
	s_cbranch_scc1 .Lgrpbar1_gspin

; __device__ __forceinline__ unsigned xb_ld(unsigned* p)              { return __hip_atomic_load(p, __ATOMIC_RELAXED, __HIP_MEMORY_SCOPE_AGENT); }
; __device__ __forceinline__ unsigned xb_add(unsigned* p, unsigned v) { return __hip_atomic_fetch_add(p, v, __ATOMIC_RELAXED, __HIP_MEMORY_SCOPE_AGENT); }
; #define XB_SPIN(cond, bar) do { unsigned _sp = 0; while (cond) { __builtin_amdgcn_s_sleep(1); \
;     if ((++_sp & 255u) == 0u) { if (xb_ld(&(bar)[XB_TMO])) break; if (_sp > XB_SPIN_CAP) { atomicAdd(&(bar)[XB_TMO], 1u); break; } } } } while (0)
; __device__ __forceinline__ void xcd_barrier(const XcdBarrier& b) {
;     asm volatile("s_waitcnt vmcnt(0)" ::: "memory");
;     __syncthreads();
;     if (threadIdx.x == 0) {
;         unsigned* bar = b.bar;
;         __builtin_amdgcn_s_waitcnt(0);
;         unsigned nloc = b.st[0], nx = b.st[1];
;         if (nloc == 0u) { xcd_barrier_complete(bar, b.x, nloc, nx); b.st[0] = nloc; b.st[1] = nx; }
;         const unsigned old = xb_add(&bar[XB_XSUB(b.x)], 1u);
;         const unsigned gen = old / nloc;
;         if (old + 1u == (gen + 1u) * nloc) {
;             __builtin_amdgcn_fence(__ATOMIC_RELEASE, "agent");
;             asm volatile("s_waitcnt vmcnt(0)" ::: "memory");
;             const unsigned og = xb_add(&bar[XB_TOP], 1u);
;             const unsigned tg = og / nx;
;             if (og + 1u == (tg + 1u) * nx) xb_add(&bar[XB_TOPGEN], 1u);
;             else XB_SPIN(xb_ld(&bar[XB_TOPGEN]) == tg, bar);
;             __builtin_amdgcn_fence(__ATOMIC_ACQUIRE, "agent");
;             xb_add(&bar[XB_XGEN(b.x)], 1u);
;             asm volatile("s_waitcnt vmcnt(0)" ::: "memory");
;         } else {
;             XB_SPIN(xb_ld(&bar[XB_XGEN(b.x)]) == gen, bar);
;             __builtin_amdgcn_fence(__ATOMIC_ACQUIRE, "agent");
;             asm volatile("s_waitcnt vmcnt(0)" ::: "memory");
;         }
;     }
;     __syncthreads();
; }
.LBB0_902:
	s_cmp_lt_i32 s19, 9
	s_cbranch_scc1 .LBB0_956
	s_waitcnt vmcnt(0)
	s_waitcnt vmcnt(0) lgkmcnt(0)
	s_barrier
	s_mov_b64 s[0:1], exec
	v_readlane_b32 s2, v247, 37
	v_readlane_b32 s3, v247, 38
	s_and_b64 s[2:3], s[0:1], s[2:3]
	s_mov_b64 exec, s[2:3]
	s_cbranch_execz .LBB0_955
	v_readlane_b32 s5, v247, 36
	s_and_b32 s2, s90, 31
	s_lshl_b32 s2, s2, 6
	s_add_u32 s2, s62, s2
	s_addc_u32 s3, s63, 0
	s_add_u32 s6, s2, 0xa000
	s_addc_u32 s7, s3, 0
	s_add_u32 s2, s2, 0x9000
	s_addc_u32 s3, s3, 0
	s_and_b32 s5, s5, 7
	s_lshl_b32 s5, s5, 2
	s_lshl_b32 s5, 8, s5
	v_mov_b32_e32 v1, 0
	global_load_dword v3, v1, s[6:7] sc1
	v_mov_b32_e32 v2, 1
	s_mov_b32 s4, 0
	s_add_u32 s6, s62, 0xc000
	s_addc_u32 s7, s63, 0
	s_waitcnt vmcnt(0) lgkmcnt(0)
	v_cmp_eq_u32_e32 vcc, s5, v3
	s_cbranch_vccnz .Lgrpbar0_same
	buffer_wbl2 sc1
	s_waitcnt vmcnt(0)
